# LN3: row prefetch + hoisted gain/bias/b_in combined with the hand-written finalize, wig columns streamed from LDS three columns ahead (no load waits in the loop body, no exposed LDS latency)
# speedup vs baseline: 1.0089x; 1.0039x over previous
; __global__ void __launch_bounds__(NT, 2) fwd(const Args args) {
;     ...
;             const float* g = A.in[17] + ((size_t)L * 3 + 2) * D; const float* bb = A.in[18] + ((size_t)L * 3 + 2) * D; const bf16* X = WSP(bf16, WS_XB);
;             if (L + 1 < DEPTH) { stage_wig(A, F, L + 1); __syncthreads(); }
;             int m0, m1; row_range(F, m0, m1);
;             for (int m = m0; m < m1; m += 4) { u32x4 r[4][2];
; #pragma unroll
;                 for (int q = 0; q < 4; ++q) { const int mm = (m + q < m1) ? m + q : m1 - 1; row_raw(X + (size_t)mm * D, F.lane, r[q]); }
.LBB0_1693:
	v_mov_b32_e32 v1, s6
	v_lshl_add_u32 v1, s8, 3, v1
	v_readlane_b32 s12, v253, 53
	v_readlane_b32 s8, v253, 52
	s_nop 0
	v_min_i32_e32 v3, s12, v1
	v_mul_lo_u32 v4, s8, v1
	v_readfirstlane_b32 s11, v3
	v_readfirstlane_b32 s16, v4
	v_add_u32_e32 v3, v4, v3
	v_mov_b32_e32 v4, s8
	v_cmp_gt_i32_e32 vcc, s12, v1
	v_readfirstlane_b32 s6, v3
	s_nop 0
	v_addc_co_u32_e32 v1, vcc, v3, v4, vcc
	v_cmp_ge_i32_e32 vcc, v3, v1
	s_and_b64 s[12:13], vcc, exec
	v_readfirstlane_b32 s8, v1
	s_cbranch_scc1 .LBB0_1723
	s_mul_hi_i32 s12, s10, 0x3000
	s_mulk_i32 s10, 0x3000
	s_add_u32 s10, s10, 0x2000
	s_addc_u32 s12, s12, 0
	v_lshlrev_b32_e32 v4, 3, v0
	s_waitcnt lgkmcnt(0)
	s_add_u32 s14, s40, s10
	v_ashrrev_i32_e32 v5, 31, v4
	s_addc_u32 s15, s41, s12
	v_lshlrev_b64 v[6:7], 1, v[4:5]
	s_add_u32 s18, s42, s10
	v_lshl_add_u64 v[8:9], s[58:59], 0, v[6:7]
	s_mov_b64 s[26:27], 0xb880000
	s_addc_u32 s19, s43, s12
	v_lshl_add_u64 v[52:53], v[8:9], 0, s[26:27]
	v_lshlrev_b64 v[54:55], 2, v[4:5]
	s_mul_hi_i32 s13, s7, 0x6820
	s_mul_i32 s26, s7, 0x6820
	s_ashr_i32 s7, s6, 31
	s_add_i32 s12, s8, -1
	v_lshl_add_u64 v[56:57], s[14:15], 0, v[54:55]
	s_lshl_b64 s[14:15], s[6:7], 12
	s_add_u32 s14, s56, s14
	v_lshl_add_u64 v[58:59], s[18:19], 0, v[54:55]
	s_addc_u32 s15, s57, s15
	s_lshl_b64 s[18:19], s[6:7], 5
	v_ashrrev_i32_e32 v1, 31, v0
	s_add_u32 s18, s18, 0x1b000000
	s_addc_u32 s19, s19, 0
	v_lshlrev_b64 v[4:5], 2, v[0:1]
	v_lshl_add_u64 v[60:61], s[18:19], 0, v[4:5]
	s_lshl_b64 s[18:19], s[6:7], 11
	s_add_i32 s7, s11, s16
	s_add_i32 s10, s7, 3
	s_ashr_i32 s11, s10, 31
	s_lshl_b64 s[16:17], s[10:11], 5
	s_add_u32 s16, s16, 0x1b000000
	s_addc_u32 s17, s17, 0
	s_add_i32 s28, s7, 1
	v_lshl_add_u64 v[64:65], s[16:17], 0, v[4:5]
	s_lshl_b64 s[16:17], s[10:11], 11
	s_ashr_i32 s29, s28, 31
	v_lshl_add_u64 v[66:67], s[16:17], 0, v[6:7]
	s_lshl_b64 s[16:17], s[28:29], 12
	s_add_u32 s16, s56, s16
	s_addc_u32 s17, s57, s17
	s_lshl_b64 s[10:11], s[10:11], 12
	v_lshl_add_u64 v[62:63], s[18:19], 0, v[6:7]
	s_add_u32 s18, s56, s10
	s_addc_u32 s19, s57, s11
	s_add_i32 s10, s7, 2
	s_ashr_i32 s11, s10, 31
	s_lshl_b64 s[34:35], s[10:11], 5
	s_add_u32 s34, s34, 0x1b000000
	s_addc_u32 s35, s35, 0
	v_lshl_add_u64 v[68:69], s[34:35], 0, v[4:5]
	s_lshl_b64 s[34:35], s[10:11], 11
	v_lshl_add_u64 v[70:71], s[34:35], 0, v[6:7]
	s_lshl_b64 s[34:35], s[28:29], 11
	s_lshl_b64 s[10:11], s[10:11], 12
	v_lshl_add_u64 v[72:73], s[34:35], 0, v[6:7]
	s_add_u32 s34, s56, s10
	s_addc_u32 s35, s57, s11
	s_lshl_b64 s[10:11], s[28:29], 5
	s_add_u32 s10, s10, 0x1b000000
	s_addc_u32 s11, s11, 0
	v_lshlrev_b32_e32 v3, 5, v0
	v_cmp_gt_i32_e64 s[38:39], 8, v0
	v_cmp_eq_u32_e64 s[40:41], 1, v0
	v_cmp_eq_u32_e64 s[42:43], 2, v0
	v_cmp_eq_u32_e64 s[44:45], 3, v0
	v_cmp_eq_u32_e64 s[46:47], 4, v0
	v_cmp_eq_u32_e64 s[48:49], 5, v0
	v_cmp_eq_u32_e64 s[50:51], 6, v0
	v_cmp_eq_u32_e64 s[52:53], 7, v0
	v_lshl_add_u64 v[74:75], s[10:11], 0, v[4:5]
	v_add_u32_e32 v94, 0x12000, v3
	global_load_dwordx4 v[104:107], v[56:57], off
	global_load_dwordx4 v[108:111], v[56:57], off offset:16
	global_load_dwordx4 v[112:115], v[56:57], off offset:2048
	global_load_dwordx4 v[116:119], v[56:57], off offset:2064
	global_load_dwordx4 v[120:123], v[58:59], off
	global_load_dwordx4 v[124:127], v[58:59], off offset:16
	global_load_dwordx4 v[128:131], v[58:59], off offset:2048
	global_load_dwordx4 v[132:135], v[58:59], off offset:2064
	s_and_b64 vcc, exec, s[4:5]
	s_cbranch_vccnz .Lpf3_nobin
	s_load_dwordx2 s[66:67], s[2:3], 0x50
	s_waitcnt lgkmcnt(0)
	s_add_u32 s66, s66, s26
	s_addc_u32 s67, s67, s13
	s_add_u32 s66, s66, 0x3000
	s_addc_u32 s67, s67, 0
	v_lshl_add_u64 v[170:171], v[0:1], 2, s[66:67]
	global_load_dword v168, v[170:171], off

; #define LAS __attribute__((address_space(3)))
; __device__ __forceinline__ float wave_sum(float v) { return rdlane(dpp_sum63(v), 63); }
; __device__ __forceinline__ void row_finalize(CArgs& A, Frame& F, int m, const f32x4 (&v)[4], int Ln) {
;     row_store_bf(WSP(bf16, WS_X) + (size_t)m * D, F.lane, v);
;     const LAS float* wig = (const LAS float*)(F.lds + WIG_OFF); const float* b_in = A.in[10] + (size_t)Ln * DIN + 3072;
;     float r[8];
; #pragma unroll
;     for (int c = 0; c < 8; ++c) { float s = 0.f;
; #pragma unroll
;         for (int j = 0; j < 4; ++j) { const f32x4 w = *(const LAS f32x4*)(wig + c * 1024 + RCOL(F.lane, j)); s += (v[j][0] * w[0] + v[j][1] * w[1]) + (v[j][2] * w[2] + v[j][3] * w[3]); }
;         r[c] = wave_sum(s); if (c & 1) asm volatile("" ::: "memory"); }
.LBB0_1701:
	ds_read_b128 v[172:175], v94 offset:0
	ds_read_b128 v[176:179], v94 offset:16
	ds_read_b128 v[180:183], v94 offset:2048
	ds_read_b128 v[184:187], v94 offset:2064
	ds_read_b128 v[202:205], v94 offset:4096
	ds_read_b128 v[206:209], v94 offset:4112
	ds_read_b128 v[210:213], v94 offset:6144
	ds_read_b128 v[214:217], v94 offset:6160
	ds_read_b128 v[218:221], v94 offset:8192
	ds_read_b128 v[222:225], v94 offset:8208
	ds_read_b128 v[188:191], v94 offset:10240
	ds_read_b128 v[192:195], v94 offset:10256
	v_lshl_add_u64 v[238:239], s[58:59], 0, v[62:63]
	s_mov_b64 s[10:11], 0x7680000
	v_cvt_pk_bf16_f32 v240, v32, v33
	v_cvt_pk_bf16_f32 v241, v34, v35
	v_cvt_pk_bf16_f32 v242, v28, v29
	v_cvt_pk_bf16_f32 v243, v30, v31
	v_lshl_add_u64 v[238:239], v[238:239], 0, s[10:11]
	v_cvt_pk_bf16_f32 v244, v44, v45
	v_cvt_pk_bf16_f32 v245, v46, v47
	v_cvt_pk_bf16_f32 v246, v36, v37
	v_cvt_pk_bf16_f32 v247, v38, v39
	global_store_dwordx4 v[238:239], v[240:243], off
	global_store_dwordx4 v[238:239], v[244:247], off offset:1024
	v_lshl_add_u64 v[196:197], s[58:59], 0, v[60:61]
	s_waitcnt lgkmcnt(8)
	v_mul_f32_e32 v249, v33, v173
	v_mul_f32_e32 v250, v35, v175
	v_fmac_f32_e32 v249, v32, v172
	v_fmac_f32_e32 v250, v34, v174
	v_add_f32_e32 v249, v249, v250
	v_add_f32_e32 v227, 0, v249
	v_mul_f32_e32 v249, v29, v177
	v_mul_f32_e32 v250, v31, v179
	v_fmac_f32_e32 v249, v28, v176
	v_fmac_f32_e32 v250, v30, v178
	v_add_f32_e32 v249, v249, v250
	v_add_f32_e32 v227, v227, v249
	v_mul_f32_e32 v249, v45, v181
	v_mul_f32_e32 v250, v47, v183
	v_fmac_f32_e32 v249, v44, v180
	v_fmac_f32_e32 v250, v46, v182
	v_add_f32_e32 v249, v249, v250
	v_add_f32_e32 v227, v227, v249
	v_mul_f32_e32 v249, v37, v185
	v_mul_f32_e32 v250, v39, v187
	v_fmac_f32_e32 v249, v36, v184
	v_fmac_f32_e32 v250, v38, v186
	v_add_f32_e32 v249, v249, v250
	v_add_f32_e32 v227, v227, v249
	ds_read_b128 v[172:175], v94 offset:12288
	ds_read_b128 v[176:179], v94 offset:12304
	ds_read_b128 v[180:183], v94 offset:14336
	ds_read_b128 v[184:187], v94 offset:14352
	s_waitcnt lgkmcnt(8)
	v_mul_f32_e32 v249, v33, v203
	v_mul_f32_e32 v250, v35, v205
	v_fmac_f32_e32 v249, v32, v202
	v_fmac_f32_e32 v250, v34, v204
	v_add_f32_e32 v249, v249, v250
	v_add_f32_e32 v228, 0, v249
	v_mul_f32_e32 v249, v29, v207
	v_mul_f32_e32 v250, v31, v209
	v_fmac_f32_e32 v249, v28, v206
	v_fmac_f32_e32 v250, v30, v208
	v_add_f32_e32 v249, v249, v250
	v_add_f32_e32 v228, v228, v249
	v_mul_f32_e32 v249, v45, v211
	v_mul_f32_e32 v250, v47, v213
	v_fmac_f32_e32 v249, v44, v210
	v_fmac_f32_e32 v250, v46, v212
	v_add_f32_e32 v249, v249, v250
	v_add_f32_e32 v228, v228, v249
	v_mul_f32_e32 v249, v37, v215
	v_mul_f32_e32 v250, v39, v217
	v_fmac_f32_e32 v249, v36, v214
	v_fmac_f32_e32 v250, v38, v216
	v_add_f32_e32 v249, v249, v250
	v_add_f32_e32 v228, v228, v249
	ds_read_b128 v[202:205], v94 offset:16384
	ds_read_b128 v[206:209], v94 offset:16400
	ds_read_b128 v[210:213], v94 offset:18432
	ds_read_b128 v[214:217], v94 offset:18448
	s_waitcnt lgkmcnt(8)
	v_mul_f32_e32 v249, v33, v219
	v_mul_f32_e32 v250, v35, v221
	v_fmac_f32_e32 v249, v32, v218
	v_fmac_f32_e32 v250, v34, v220
	v_add_f32_e32 v249, v249, v250
	v_add_f32_e32 v229, 0, v249
	v_mul_f32_e32 v249, v29, v223
	v_mul_f32_e32 v250, v31, v225
	v_fmac_f32_e32 v249, v28, v222
	v_fmac_f32_e32 v250, v30, v224
	v_add_f32_e32 v249, v249, v250
	v_add_f32_e32 v229, v229, v249
	v_mul_f32_e32 v249, v45, v189
	v_mul_f32_e32 v250, v47, v191
	v_fmac_f32_e32 v249, v44, v188
	v_fmac_f32_e32 v250, v46, v190
	v_add_f32_e32 v249, v249, v250
	v_add_f32_e32 v229, v229, v249
	v_mul_f32_e32 v249, v37, v193
	v_mul_f32_e32 v250, v39, v195
	v_fmac_f32_e32 v249, v36, v192
	v_fmac_f32_e32 v250, v38, v194
	v_add_f32_e32 v249, v249, v250
	v_add_f32_e32 v229, v229, v249
	ds_read_b128 v[218:221], v94 offset:20480
	ds_read_b128 v[222:225], v94 offset:20496
	ds_read_b128 v[188:191], v94 offset:22528
	ds_read_b128 v[192:195], v94 offset:22544
	s_waitcnt lgkmcnt(8)
	v_mul_f32_e32 v249, v33, v173
	v_mul_f32_e32 v250, v35, v175
	v_fmac_f32_e32 v249, v32, v172
	v_fmac_f32_e32 v250, v34, v174
	v_add_f32_e32 v249, v249, v250
	v_add_f32_e32 v230, 0, v249
	v_mul_f32_e32 v249, v29, v177
	v_mul_f32_e32 v250, v31, v179
	v_fmac_f32_e32 v249, v28, v176
	v_fmac_f32_e32 v250, v30, v178
	v_add_f32_e32 v249, v249, v250
	v_add_f32_e32 v230, v230, v249
	v_mul_f32_e32 v249, v45, v181
	v_mul_f32_e32 v250, v47, v183
	v_fmac_f32_e32 v249, v44, v180
	v_fmac_f32_e32 v250, v46, v182
	v_add_f32_e32 v249, v249, v250
	v_add_f32_e32 v230, v230, v249
	v_mul_f32_e32 v249, v37, v185
	v_mul_f32_e32 v250, v39, v187
	v_fmac_f32_e32 v249, v36, v184
	v_fmac_f32_e32 v250, v38, v186
	v_add_f32_e32 v249, v249, v250
	v_add_f32_e32 v230, v230, v249
	ds_read_b128 v[172:175], v94 offset:24576
	ds_read_b128 v[176:179], v94 offset:24592
	ds_read_b128 v[180:183], v94 offset:26624
	ds_read_b128 v[184:187], v94 offset:26640
	s_waitcnt lgkmcnt(8)
	v_mul_f32_e32 v249, v33, v203
	v_mul_f32_e32 v250, v35, v205
	v_fmac_f32_e32 v249, v32, v202
	v_fmac_f32_e32 v250, v34, v204
	v_add_f32_e32 v249, v249, v250
	v_add_f32_e32 v231, 0, v249
	v_mul_f32_e32 v249, v29, v207
	v_mul_f32_e32 v250, v31, v209
	v_fmac_f32_e32 v249, v28, v206
	v_fmac_f32_e32 v250, v30, v208
	v_add_f32_e32 v249, v249, v250
	v_add_f32_e32 v231, v231, v249
	v_mul_f32_e32 v249, v45, v211
	v_mul_f32_e32 v250, v47, v213
	v_fmac_f32_e32 v249, v44, v210
	v_fmac_f32_e32 v250, v46, v212
	v_add_f32_e32 v249, v249, v250
	v_add_f32_e32 v231, v231, v249
	v_mul_f32_e32 v249, v37, v215
	v_mul_f32_e32 v250, v39, v217
	v_fmac_f32_e32 v249, v36, v214
	v_fmac_f32_e32 v250, v38, v216
	v_add_f32_e32 v249, v249, v250
	v_add_f32_e32 v231, v231, v249
	ds_read_b128 v[202:205], v94 offset:28672
	ds_read_b128 v[206:209], v94 offset:28688
	ds_read_b128 v[210:213], v94 offset:30720
	ds_read_b128 v[214:217], v94 offset:30736
	s_waitcnt lgkmcnt(8)
; #define LAS __attribute__((address_space(3)))
; __device__ __forceinline__ float wave_sum(float v) { return rdlane(dpp_sum63(v), 63); }
; __device__ __forceinline__ void row_finalize(CArgs& A, Frame& F, int m, const f32x4 (&v)[4], int Ln) {
;     ...
;     for (int c = 0; c < 8; ++c) { float s = 0.f;
; #pragma unroll
;         for (int j = 0; j < 4; ++j) { const f32x4 w = *(const LAS f32x4*)(wig + c * 1024 + RCOL(F.lane, j)); s += (v[j][0] * w[0] + v[j][1] * w[1]) + (v[j][2] * w[2] + v[j][3] * w[3]); }
;         r[c] = wave_sum(s); if (c & 1) asm volatile("" ::: "memory"); }
;     if (F.lane < 8) { float x = r[0];
; #pragma unroll
;         for (int c = 1; c < 8; ++c) x = (F.lane == c) ? r[c] : x;
;         WSP(float, WS_IGFG)[(size_t)m * 8 + F.lane] = x + b_in[F.lane]; }
	v_mul_f32_e32 v249, v33, v219
	v_mul_f32_e32 v250, v35, v221
	v_fmac_f32_e32 v249, v32, v218
	v_fmac_f32_e32 v250, v34, v220
	v_add_f32_e32 v249, v249, v250
	v_add_f32_e32 v232, 0, v249
	v_mul_f32_e32 v249, v29, v223
	v_mul_f32_e32 v250, v31, v225
	v_fmac_f32_e32 v249, v28, v222
	v_fmac_f32_e32 v250, v30, v224
	v_add_f32_e32 v249, v249, v250
	v_add_f32_e32 v232, v232, v249
	v_mul_f32_e32 v249, v45, v189
	v_mul_f32_e32 v250, v47, v191
	v_fmac_f32_e32 v249, v44, v188
	v_fmac_f32_e32 v250, v46, v190
	v_add_f32_e32 v249, v249, v250
	v_add_f32_e32 v232, v232, v249
	v_mul_f32_e32 v249, v37, v193
	v_mul_f32_e32 v250, v39, v195
	v_fmac_f32_e32 v249, v36, v192
	v_fmac_f32_e32 v250, v38, v194
	v_add_f32_e32 v249, v249, v250
	v_add_f32_e32 v232, v232, v249
	s_waitcnt lgkmcnt(4)
	v_mul_f32_e32 v249, v33, v173
	v_mul_f32_e32 v250, v35, v175
	v_fmac_f32_e32 v249, v32, v172
	v_fmac_f32_e32 v250, v34, v174
	v_add_f32_e32 v249, v249, v250
	v_add_f32_e32 v233, 0, v249
	v_mul_f32_e32 v249, v29, v177
	v_mul_f32_e32 v250, v31, v179
	v_fmac_f32_e32 v249, v28, v176
	v_fmac_f32_e32 v250, v30, v178
	v_add_f32_e32 v249, v249, v250
	v_add_f32_e32 v233, v233, v249
	v_mul_f32_e32 v249, v45, v181
	v_mul_f32_e32 v250, v47, v183
	v_fmac_f32_e32 v249, v44, v180
	v_fmac_f32_e32 v250, v46, v182
	v_add_f32_e32 v249, v249, v250
	v_add_f32_e32 v233, v233, v249
	v_mul_f32_e32 v249, v37, v185
	v_mul_f32_e32 v250, v39, v187
	v_fmac_f32_e32 v249, v36, v184
	v_fmac_f32_e32 v250, v38, v186
	v_add_f32_e32 v249, v249, v250
	v_add_f32_e32 v233, v233, v249
	s_waitcnt lgkmcnt(0)
	v_mul_f32_e32 v249, v33, v203
	v_mul_f32_e32 v250, v35, v205
	v_fmac_f32_e32 v249, v32, v202
	v_fmac_f32_e32 v250, v34, v204
	v_add_f32_e32 v249, v249, v250
	v_add_f32_e32 v248, 0, v249
	v_mul_f32_e32 v249, v29, v207
	v_mul_f32_e32 v250, v31, v209
	v_fmac_f32_e32 v249, v28, v206
	v_fmac_f32_e32 v250, v30, v208
	v_add_f32_e32 v249, v249, v250
	v_add_f32_e32 v248, v248, v249
	v_mul_f32_e32 v249, v45, v211
	v_mul_f32_e32 v250, v47, v213
	v_fmac_f32_e32 v249, v44, v210
	v_fmac_f32_e32 v250, v46, v212
	v_add_f32_e32 v249, v249, v250
	v_add_f32_e32 v248, v248, v249
	v_mul_f32_e32 v249, v37, v215
	v_mul_f32_e32 v250, v39, v217
	v_fmac_f32_e32 v249, v36, v214
	v_fmac_f32_e32 v250, v38, v216
	v_add_f32_e32 v249, v249, v250
	v_add_f32_e32 v248, v248, v249
	v_add_f32_dpp v227, v227, v227 quad_perm:[1,0,3,2] row_mask:0xf bank_mask:0xf bound_ctrl:1
	v_add_f32_dpp v228, v228, v228 quad_perm:[1,0,3,2] row_mask:0xf bank_mask:0xf bound_ctrl:1
	v_add_f32_dpp v229, v229, v229 quad_perm:[1,0,3,2] row_mask:0xf bank_mask:0xf bound_ctrl:1
	v_add_f32_dpp v230, v230, v230 quad_perm:[1,0,3,2] row_mask:0xf bank_mask:0xf bound_ctrl:1
	v_add_f32_dpp v231, v231, v231 quad_perm:[1,0,3,2] row_mask:0xf bank_mask:0xf bound_ctrl:1
	v_add_f32_dpp v232, v232, v232 quad_perm:[1,0,3,2] row_mask:0xf bank_mask:0xf bound_ctrl:1
	v_add_f32_dpp v233, v233, v233 quad_perm:[1,0,3,2] row_mask:0xf bank_mask:0xf bound_ctrl:1
	v_add_f32_dpp v248, v248, v248 quad_perm:[1,0,3,2] row_mask:0xf bank_mask:0xf bound_ctrl:1
	v_add_f32_dpp v227, v227, v227 quad_perm:[2,3,0,1] row_mask:0xf bank_mask:0xf bound_ctrl:1
	v_add_f32_dpp v228, v228, v228 quad_perm:[2,3,0,1] row_mask:0xf bank_mask:0xf bound_ctrl:1
	v_add_f32_dpp v229, v229, v229 quad_perm:[2,3,0,1] row_mask:0xf bank_mask:0xf bound_ctrl:1
	v_add_f32_dpp v230, v230, v230 quad_perm:[2,3,0,1] row_mask:0xf bank_mask:0xf bound_ctrl:1
	v_add_f32_dpp v231, v231, v231 quad_perm:[2,3,0,1] row_mask:0xf bank_mask:0xf bound_ctrl:1
	v_add_f32_dpp v232, v232, v232 quad_perm:[2,3,0,1] row_mask:0xf bank_mask:0xf bound_ctrl:1
	v_add_f32_dpp v233, v233, v233 quad_perm:[2,3,0,1] row_mask:0xf bank_mask:0xf bound_ctrl:1
	v_add_f32_dpp v248, v248, v248 quad_perm:[2,3,0,1] row_mask:0xf bank_mask:0xf bound_ctrl:1
	v_add_f32_dpp v227, v227, v227 row_half_mirror row_mask:0xf bank_mask:0xf bound_ctrl:1
	v_add_f32_dpp v228, v228, v228 row_half_mirror row_mask:0xf bank_mask:0xf bound_ctrl:1
	v_add_f32_dpp v229, v229, v229 row_half_mirror row_mask:0xf bank_mask:0xf bound_ctrl:1
	v_add_f32_dpp v230, v230, v230 row_half_mirror row_mask:0xf bank_mask:0xf bound_ctrl:1
	v_add_f32_dpp v231, v231, v231 row_half_mirror row_mask:0xf bank_mask:0xf bound_ctrl:1
	v_add_f32_dpp v232, v232, v232 row_half_mirror row_mask:0xf bank_mask:0xf bound_ctrl:1
	v_add_f32_dpp v233, v233, v233 row_half_mirror row_mask:0xf bank_mask:0xf bound_ctrl:1
	v_add_f32_dpp v248, v248, v248 row_half_mirror row_mask:0xf bank_mask:0xf bound_ctrl:1
	v_add_f32_dpp v227, v227, v227 row_mirror row_mask:0xf bank_mask:0xf bound_ctrl:1
	v_add_f32_dpp v228, v228, v228 row_mirror row_mask:0xf bank_mask:0xf bound_ctrl:1
	v_add_f32_dpp v229, v229, v229 row_mirror row_mask:0xf bank_mask:0xf bound_ctrl:1
	v_add_f32_dpp v230, v230, v230 row_mirror row_mask:0xf bank_mask:0xf bound_ctrl:1
	v_add_f32_dpp v231, v231, v231 row_mirror row_mask:0xf bank_mask:0xf bound_ctrl:1
	v_add_f32_dpp v232, v232, v232 row_mirror row_mask:0xf bank_mask:0xf bound_ctrl:1
	v_add_f32_dpp v233, v233, v233 row_mirror row_mask:0xf bank_mask:0xf bound_ctrl:1
	v_add_f32_dpp v248, v248, v248 row_mirror row_mask:0xf bank_mask:0xf bound_ctrl:1
	v_add_f32_dpp v227, v227, v227 row_bcast:15 row_mask:0xa bank_mask:0xf
	v_add_f32_dpp v228, v228, v228 row_bcast:15 row_mask:0xa bank_mask:0xf
	v_add_f32_dpp v229, v229, v229 row_bcast:15 row_mask:0xa bank_mask:0xf
	v_add_f32_dpp v230, v230, v230 row_bcast:15 row_mask:0xa bank_mask:0xf
	v_add_f32_dpp v231, v231, v231 row_bcast:15 row_mask:0xa bank_mask:0xf
	v_add_f32_dpp v232, v232, v232 row_bcast:15 row_mask:0xa bank_mask:0xf
	v_add_f32_dpp v233, v233, v233 row_bcast:15 row_mask:0xa bank_mask:0xf
	v_add_f32_dpp v248, v248, v248 row_bcast:15 row_mask:0xa bank_mask:0xf
	v_add_f32_dpp v227, v227, v227 row_bcast:31 row_mask:0xc bank_mask:0xf
	v_add_f32_dpp v228, v228, v228 row_bcast:31 row_mask:0xc bank_mask:0xf
	v_add_f32_dpp v229, v229, v229 row_bcast:31 row_mask:0xc bank_mask:0xf
	v_add_f32_dpp v230, v230, v230 row_bcast:31 row_mask:0xc bank_mask:0xf
	v_add_f32_dpp v231, v231, v231 row_bcast:31 row_mask:0xc bank_mask:0xf
	v_add_f32_dpp v232, v232, v232 row_bcast:31 row_mask:0xc bank_mask:0xf
	v_add_f32_dpp v233, v233, v233 row_bcast:31 row_mask:0xc bank_mask:0xf
	v_add_f32_dpp v248, v248, v248 row_bcast:31 row_mask:0xc bank_mask:0xf
	v_readlane_b32 s29, v227, 63
	v_readlane_b32 s36, v228, 63
	v_readlane_b32 s37, v229, 63
	v_readlane_b32 s56, v230, 63
	v_readlane_b32 s57, v231, 63
	v_readlane_b32 s60, v232, 63
	v_readlane_b32 s61, v233, 63
	v_readlane_b32 s64, v248, 63
	v_writelane_b32 v251, s29, 0
	v_writelane_b32 v251, s36, 1
	v_writelane_b32 v251, s37, 2
	v_writelane_b32 v251, s56, 3
	v_writelane_b32 v251, s57, 4
	v_writelane_b32 v251, s60, 5
	v_writelane_b32 v251, s61, 6
	v_writelane_b32 v251, s64, 7
	s_and_saveexec_b64 s[10:11], s[38:39]
	v_add_f32_e32 v251, v251, v168
	global_store_dword v[196:197], v251, off

; #define LAS __attribute__((address_space(3)))
; __device__ __forceinline__ float wave_sum(float v) { return rdlane(dpp_sum63(v), 63); }
; __device__ __forceinline__ void row_finalize(CArgs& A, Frame& F, int m, const f32x4 (&v)[4], int Ln) {
;     row_store_bf(WSP(bf16, WS_X) + (size_t)m * D, F.lane, v);
;     const LAS float* wig = (const LAS float*)(F.lds + WIG_OFF); const float* b_in = A.in[10] + (size_t)Ln * DIN + 3072;
;     float r[8];
; #pragma unroll
;     for (int c = 0; c < 8; ++c) { float s = 0.f;
; #pragma unroll
;         for (int j = 0; j < 4; ++j) { const f32x4 w = *(const LAS f32x4*)(wig + c * 1024 + RCOL(F.lane, j)); s += (v[j][0] * w[0] + v[j][1] * w[1]) + (v[j][2] * w[2] + v[j][3] * w[3]); }
;         r[c] = wave_sum(s); if (c & 1) asm volatile("" ::: "memory"); }
.LBB0_1706:
	s_andn2_b64 vcc, exec, s[10:11]
	s_cbranch_vccnz .LBB0_1710
	ds_read_b128 v[172:175], v94 offset:0
	ds_read_b128 v[176:179], v94 offset:16
	ds_read_b128 v[180:183], v94 offset:2048
	ds_read_b128 v[184:187], v94 offset:2064
	ds_read_b128 v[202:205], v94 offset:4096
	ds_read_b128 v[206:209], v94 offset:4112
	ds_read_b128 v[210:213], v94 offset:6144
	ds_read_b128 v[214:217], v94 offset:6160
	ds_read_b128 v[218:221], v94 offset:8192
	ds_read_b128 v[222:225], v94 offset:8208
	ds_read_b128 v[188:191], v94 offset:10240
	ds_read_b128 v[192:195], v94 offset:10256
	v_lshl_add_u64 v[238:239], s[58:59], 0, v[72:73]
	s_mov_b64 s[10:11], 0x7680000
	v_cvt_pk_bf16_f32 v240, v24, v25
	v_cvt_pk_bf16_f32 v241, v26, v27
	v_cvt_pk_bf16_f32 v242, v20, v21
	v_cvt_pk_bf16_f32 v243, v22, v23
	v_lshl_add_u64 v[238:239], v[238:239], 0, s[10:11]
	v_cvt_pk_bf16_f32 v244, v28, v29
	v_cvt_pk_bf16_f32 v245, v30, v31
	v_cvt_pk_bf16_f32 v246, v32, v33
	v_cvt_pk_bf16_f32 v247, v34, v35
	global_store_dwordx4 v[238:239], v[240:243], off
	global_store_dwordx4 v[238:239], v[244:247], off offset:1024
	v_lshl_add_u64 v[196:197], s[58:59], 0, v[74:75]
	s_waitcnt lgkmcnt(8)
	v_mul_f32_e32 v249, v25, v173
	v_mul_f32_e32 v250, v27, v175
	v_fmac_f32_e32 v249, v24, v172
	v_fmac_f32_e32 v250, v26, v174
	v_add_f32_e32 v249, v249, v250
	v_add_f32_e32 v227, 0, v249
	v_mul_f32_e32 v249, v21, v177
	v_mul_f32_e32 v250, v23, v179
	v_fmac_f32_e32 v249, v20, v176
	v_fmac_f32_e32 v250, v22, v178
	v_add_f32_e32 v249, v249, v250
	v_add_f32_e32 v227, v227, v249
	v_mul_f32_e32 v249, v29, v181
	v_mul_f32_e32 v250, v31, v183
	v_fmac_f32_e32 v249, v28, v180
	v_fmac_f32_e32 v250, v30, v182
	v_add_f32_e32 v249, v249, v250
	v_add_f32_e32 v227, v227, v249
	v_mul_f32_e32 v249, v33, v185
	v_mul_f32_e32 v250, v35, v187
	v_fmac_f32_e32 v249, v32, v184
	v_fmac_f32_e32 v250, v34, v186
	v_add_f32_e32 v249, v249, v250
	v_add_f32_e32 v227, v227, v249
	ds_read_b128 v[172:175], v94 offset:12288
	ds_read_b128 v[176:179], v94 offset:12304
	ds_read_b128 v[180:183], v94 offset:14336
	ds_read_b128 v[184:187], v94 offset:14352
	s_waitcnt lgkmcnt(8)
	v_mul_f32_e32 v249, v25, v203
	v_mul_f32_e32 v250, v27, v205
	v_fmac_f32_e32 v249, v24, v202
	v_fmac_f32_e32 v250, v26, v204
	v_add_f32_e32 v249, v249, v250
	v_add_f32_e32 v228, 0, v249
	v_mul_f32_e32 v249, v21, v207
	v_mul_f32_e32 v250, v23, v209
	v_fmac_f32_e32 v249, v20, v206
	v_fmac_f32_e32 v250, v22, v208
	v_add_f32_e32 v249, v249, v250
	v_add_f32_e32 v228, v228, v249
	v_mul_f32_e32 v249, v29, v211
	v_mul_f32_e32 v250, v31, v213
	v_fmac_f32_e32 v249, v28, v210
	v_fmac_f32_e32 v250, v30, v212
	v_add_f32_e32 v249, v249, v250
	v_add_f32_e32 v228, v228, v249
	v_mul_f32_e32 v249, v33, v215
	v_mul_f32_e32 v250, v35, v217
	v_fmac_f32_e32 v249, v32, v214
	v_fmac_f32_e32 v250, v34, v216
	v_add_f32_e32 v249, v249, v250
	v_add_f32_e32 v228, v228, v249
	ds_read_b128 v[202:205], v94 offset:16384
	ds_read_b128 v[206:209], v94 offset:16400
	ds_read_b128 v[210:213], v94 offset:18432
	ds_read_b128 v[214:217], v94 offset:18448
	s_waitcnt lgkmcnt(8)
	v_mul_f32_e32 v249, v25, v219
	v_mul_f32_e32 v250, v27, v221
	v_fmac_f32_e32 v249, v24, v218
	v_fmac_f32_e32 v250, v26, v220
	v_add_f32_e32 v249, v249, v250
	v_add_f32_e32 v229, 0, v249
	v_mul_f32_e32 v249, v21, v223
	v_mul_f32_e32 v250, v23, v225
	v_fmac_f32_e32 v249, v20, v222
	v_fmac_f32_e32 v250, v22, v224
	v_add_f32_e32 v249, v249, v250
	v_add_f32_e32 v229, v229, v249
	v_mul_f32_e32 v249, v29, v189
	v_mul_f32_e32 v250, v31, v191
	v_fmac_f32_e32 v249, v28, v188
	v_fmac_f32_e32 v250, v30, v190
	v_add_f32_e32 v249, v249, v250
	v_add_f32_e32 v229, v229, v249
	v_mul_f32_e32 v249, v33, v193
	v_mul_f32_e32 v250, v35, v195
	v_fmac_f32_e32 v249, v32, v192
	v_fmac_f32_e32 v250, v34, v194
	v_add_f32_e32 v249, v249, v250
	v_add_f32_e32 v229, v229, v249
	ds_read_b128 v[218:221], v94 offset:20480
	ds_read_b128 v[222:225], v94 offset:20496
	ds_read_b128 v[188:191], v94 offset:22528
	ds_read_b128 v[192:195], v94 offset:22544
	s_waitcnt lgkmcnt(8)
	v_mul_f32_e32 v249, v25, v173
	v_mul_f32_e32 v250, v27, v175
	v_fmac_f32_e32 v249, v24, v172
	v_fmac_f32_e32 v250, v26, v174
	v_add_f32_e32 v249, v249, v250
	v_add_f32_e32 v230, 0, v249
	v_mul_f32_e32 v249, v21, v177
	v_mul_f32_e32 v250, v23, v179
	v_fmac_f32_e32 v249, v20, v176
	v_fmac_f32_e32 v250, v22, v178
	v_add_f32_e32 v249, v249, v250
	v_add_f32_e32 v230, v230, v249
	v_mul_f32_e32 v249, v29, v181
	v_mul_f32_e32 v250, v31, v183
	v_fmac_f32_e32 v249, v28, v180
	v_fmac_f32_e32 v250, v30, v182
	v_add_f32_e32 v249, v249, v250
	v_add_f32_e32 v230, v230, v249
	v_mul_f32_e32 v249, v33, v185
	v_mul_f32_e32 v250, v35, v187
	v_fmac_f32_e32 v249, v32, v184
	v_fmac_f32_e32 v250, v34, v186
	v_add_f32_e32 v249, v249, v250
	v_add_f32_e32 v230, v230, v249
	ds_read_b128 v[172:175], v94 offset:24576
	ds_read_b128 v[176:179], v94 offset:24592
	ds_read_b128 v[180:183], v94 offset:26624
	ds_read_b128 v[184:187], v94 offset:26640
	s_waitcnt lgkmcnt(8)
	v_mul_f32_e32 v249, v25, v203
	v_mul_f32_e32 v250, v27, v205
	v_fmac_f32_e32 v249, v24, v202
	v_fmac_f32_e32 v250, v26, v204
	v_add_f32_e32 v249, v249, v250
	v_add_f32_e32 v231, 0, v249
	v_mul_f32_e32 v249, v21, v207
	v_mul_f32_e32 v250, v23, v209
	v_fmac_f32_e32 v249, v20, v206
	v_fmac_f32_e32 v250, v22, v208
	v_add_f32_e32 v249, v249, v250
	v_add_f32_e32 v231, v231, v249
	v_mul_f32_e32 v249, v29, v211
	v_mul_f32_e32 v250, v31, v213
	v_fmac_f32_e32 v249, v28, v210
	v_fmac_f32_e32 v250, v30, v212
	v_add_f32_e32 v249, v249, v250
	v_add_f32_e32 v231, v231, v249
	v_mul_f32_e32 v249, v33, v215
	v_mul_f32_e32 v250, v35, v217
	v_fmac_f32_e32 v249, v32, v214
	v_fmac_f32_e32 v250, v34, v216
	v_add_f32_e32 v249, v249, v250
	v_add_f32_e32 v231, v231, v249
	ds_read_b128 v[202:205], v94 offset:28672
	ds_read_b128 v[206:209], v94 offset:28688
	ds_read_b128 v[210:213], v94 offset:30720
	ds_read_b128 v[214:217], v94 offset:30736
	s_waitcnt lgkmcnt(8)
; #define LAS __attribute__((address_space(3)))
; __device__ __forceinline__ float wave_sum(float v) { return rdlane(dpp_sum63(v), 63); }
; __device__ __forceinline__ void row_finalize(CArgs& A, Frame& F, int m, const f32x4 (&v)[4], int Ln) {
;     ...
;     for (int c = 0; c < 8; ++c) { float s = 0.f;
; #pragma unroll
;         for (int j = 0; j < 4; ++j) { const f32x4 w = *(const LAS f32x4*)(wig + c * 1024 + RCOL(F.lane, j)); s += (v[j][0] * w[0] + v[j][1] * w[1]) + (v[j][2] * w[2] + v[j][3] * w[3]); }
;         r[c] = wave_sum(s); if (c & 1) asm volatile("" ::: "memory"); }
;     if (F.lane < 8) { float x = r[0];
; #pragma unroll
;         for (int c = 1; c < 8; ++c) x = (F.lane == c) ? r[c] : x;
;         WSP(float, WS_IGFG)[(size_t)m * 8 + F.lane] = x + b_in[F.lane]; }
	v_mul_f32_e32 v249, v25, v219
	v_mul_f32_e32 v250, v27, v221
	v_fmac_f32_e32 v249, v24, v218
	v_fmac_f32_e32 v250, v26, v220
	v_add_f32_e32 v249, v249, v250
	v_add_f32_e32 v232, 0, v249
	v_mul_f32_e32 v249, v21, v223
	v_mul_f32_e32 v250, v23, v225
	v_fmac_f32_e32 v249, v20, v222
	v_fmac_f32_e32 v250, v22, v224
	v_add_f32_e32 v249, v249, v250
	v_add_f32_e32 v232, v232, v249
	v_mul_f32_e32 v249, v29, v189
	v_mul_f32_e32 v250, v31, v191
	v_fmac_f32_e32 v249, v28, v188
	v_fmac_f32_e32 v250, v30, v190
	v_add_f32_e32 v249, v249, v250
	v_add_f32_e32 v232, v232, v249
	v_mul_f32_e32 v249, v33, v193
	v_mul_f32_e32 v250, v35, v195
	v_fmac_f32_e32 v249, v32, v192
	v_fmac_f32_e32 v250, v34, v194
	v_add_f32_e32 v249, v249, v250
	v_add_f32_e32 v232, v232, v249
	s_waitcnt lgkmcnt(4)
	v_mul_f32_e32 v249, v25, v173
	v_mul_f32_e32 v250, v27, v175
	v_fmac_f32_e32 v249, v24, v172
	v_fmac_f32_e32 v250, v26, v174
	v_add_f32_e32 v249, v249, v250
	v_add_f32_e32 v233, 0, v249
	v_mul_f32_e32 v249, v21, v177
	v_mul_f32_e32 v250, v23, v179
	v_fmac_f32_e32 v249, v20, v176
	v_fmac_f32_e32 v250, v22, v178
	v_add_f32_e32 v249, v249, v250
	v_add_f32_e32 v233, v233, v249
	v_mul_f32_e32 v249, v29, v181
	v_mul_f32_e32 v250, v31, v183
	v_fmac_f32_e32 v249, v28, v180
	v_fmac_f32_e32 v250, v30, v182
	v_add_f32_e32 v249, v249, v250
	v_add_f32_e32 v233, v233, v249
	v_mul_f32_e32 v249, v33, v185
	v_mul_f32_e32 v250, v35, v187
	v_fmac_f32_e32 v249, v32, v184
	v_fmac_f32_e32 v250, v34, v186
	v_add_f32_e32 v249, v249, v250
	v_add_f32_e32 v233, v233, v249
	s_waitcnt lgkmcnt(0)
	v_mul_f32_e32 v249, v25, v203
	v_mul_f32_e32 v250, v27, v205
	v_fmac_f32_e32 v249, v24, v202
	v_fmac_f32_e32 v250, v26, v204
	v_add_f32_e32 v249, v249, v250
	v_add_f32_e32 v248, 0, v249
	v_mul_f32_e32 v249, v21, v207
	v_mul_f32_e32 v250, v23, v209
	v_fmac_f32_e32 v249, v20, v206
	v_fmac_f32_e32 v250, v22, v208
	v_add_f32_e32 v249, v249, v250
	v_add_f32_e32 v248, v248, v249
	v_mul_f32_e32 v249, v29, v211
	v_mul_f32_e32 v250, v31, v213
	v_fmac_f32_e32 v249, v28, v210
	v_fmac_f32_e32 v250, v30, v212
	v_add_f32_e32 v249, v249, v250
	v_add_f32_e32 v248, v248, v249
	v_mul_f32_e32 v249, v33, v215
	v_mul_f32_e32 v250, v35, v217
	v_fmac_f32_e32 v249, v32, v214
	v_fmac_f32_e32 v250, v34, v216
	v_add_f32_e32 v249, v249, v250
	v_add_f32_e32 v248, v248, v249
	v_add_f32_dpp v227, v227, v227 quad_perm:[1,0,3,2] row_mask:0xf bank_mask:0xf bound_ctrl:1
	v_add_f32_dpp v228, v228, v228 quad_perm:[1,0,3,2] row_mask:0xf bank_mask:0xf bound_ctrl:1
	v_add_f32_dpp v229, v229, v229 quad_perm:[1,0,3,2] row_mask:0xf bank_mask:0xf bound_ctrl:1
	v_add_f32_dpp v230, v230, v230 quad_perm:[1,0,3,2] row_mask:0xf bank_mask:0xf bound_ctrl:1
	v_add_f32_dpp v231, v231, v231 quad_perm:[1,0,3,2] row_mask:0xf bank_mask:0xf bound_ctrl:1
	v_add_f32_dpp v232, v232, v232 quad_perm:[1,0,3,2] row_mask:0xf bank_mask:0xf bound_ctrl:1
	v_add_f32_dpp v233, v233, v233 quad_perm:[1,0,3,2] row_mask:0xf bank_mask:0xf bound_ctrl:1
	v_add_f32_dpp v248, v248, v248 quad_perm:[1,0,3,2] row_mask:0xf bank_mask:0xf bound_ctrl:1
	v_add_f32_dpp v227, v227, v227 quad_perm:[2,3,0,1] row_mask:0xf bank_mask:0xf bound_ctrl:1
	v_add_f32_dpp v228, v228, v228 quad_perm:[2,3,0,1] row_mask:0xf bank_mask:0xf bound_ctrl:1
	v_add_f32_dpp v229, v229, v229 quad_perm:[2,3,0,1] row_mask:0xf bank_mask:0xf bound_ctrl:1
	v_add_f32_dpp v230, v230, v230 quad_perm:[2,3,0,1] row_mask:0xf bank_mask:0xf bound_ctrl:1
	v_add_f32_dpp v231, v231, v231 quad_perm:[2,3,0,1] row_mask:0xf bank_mask:0xf bound_ctrl:1
	v_add_f32_dpp v232, v232, v232 quad_perm:[2,3,0,1] row_mask:0xf bank_mask:0xf bound_ctrl:1
	v_add_f32_dpp v233, v233, v233 quad_perm:[2,3,0,1] row_mask:0xf bank_mask:0xf bound_ctrl:1
	v_add_f32_dpp v248, v248, v248 quad_perm:[2,3,0,1] row_mask:0xf bank_mask:0xf bound_ctrl:1
	v_add_f32_dpp v227, v227, v227 row_half_mirror row_mask:0xf bank_mask:0xf bound_ctrl:1
	v_add_f32_dpp v228, v228, v228 row_half_mirror row_mask:0xf bank_mask:0xf bound_ctrl:1
	v_add_f32_dpp v229, v229, v229 row_half_mirror row_mask:0xf bank_mask:0xf bound_ctrl:1
	v_add_f32_dpp v230, v230, v230 row_half_mirror row_mask:0xf bank_mask:0xf bound_ctrl:1
	v_add_f32_dpp v231, v231, v231 row_half_mirror row_mask:0xf bank_mask:0xf bound_ctrl:1
	v_add_f32_dpp v232, v232, v232 row_half_mirror row_mask:0xf bank_mask:0xf bound_ctrl:1
	v_add_f32_dpp v233, v233, v233 row_half_mirror row_mask:0xf bank_mask:0xf bound_ctrl:1
	v_add_f32_dpp v248, v248, v248 row_half_mirror row_mask:0xf bank_mask:0xf bound_ctrl:1
	v_add_f32_dpp v227, v227, v227 row_mirror row_mask:0xf bank_mask:0xf bound_ctrl:1
	v_add_f32_dpp v228, v228, v228 row_mirror row_mask:0xf bank_mask:0xf bound_ctrl:1
	v_add_f32_dpp v229, v229, v229 row_mirror row_mask:0xf bank_mask:0xf bound_ctrl:1
	v_add_f32_dpp v230, v230, v230 row_mirror row_mask:0xf bank_mask:0xf bound_ctrl:1
	v_add_f32_dpp v231, v231, v231 row_mirror row_mask:0xf bank_mask:0xf bound_ctrl:1
	v_add_f32_dpp v232, v232, v232 row_mirror row_mask:0xf bank_mask:0xf bound_ctrl:1
	v_add_f32_dpp v233, v233, v233 row_mirror row_mask:0xf bank_mask:0xf bound_ctrl:1
	v_add_f32_dpp v248, v248, v248 row_mirror row_mask:0xf bank_mask:0xf bound_ctrl:1
	v_add_f32_dpp v227, v227, v227 row_bcast:15 row_mask:0xa bank_mask:0xf
	v_add_f32_dpp v228, v228, v228 row_bcast:15 row_mask:0xa bank_mask:0xf
	v_add_f32_dpp v229, v229, v229 row_bcast:15 row_mask:0xa bank_mask:0xf
	v_add_f32_dpp v230, v230, v230 row_bcast:15 row_mask:0xa bank_mask:0xf
	v_add_f32_dpp v231, v231, v231 row_bcast:15 row_mask:0xa bank_mask:0xf
	v_add_f32_dpp v232, v232, v232 row_bcast:15 row_mask:0xa bank_mask:0xf
	v_add_f32_dpp v233, v233, v233 row_bcast:15 row_mask:0xa bank_mask:0xf
	v_add_f32_dpp v248, v248, v248 row_bcast:15 row_mask:0xa bank_mask:0xf
	v_add_f32_dpp v227, v227, v227 row_bcast:31 row_mask:0xc bank_mask:0xf
	v_add_f32_dpp v228, v228, v228 row_bcast:31 row_mask:0xc bank_mask:0xf
	v_add_f32_dpp v229, v229, v229 row_bcast:31 row_mask:0xc bank_mask:0xf
	v_add_f32_dpp v230, v230, v230 row_bcast:31 row_mask:0xc bank_mask:0xf
	v_add_f32_dpp v231, v231, v231 row_bcast:31 row_mask:0xc bank_mask:0xf
	v_add_f32_dpp v232, v232, v232 row_bcast:31 row_mask:0xc bank_mask:0xf
	v_add_f32_dpp v233, v233, v233 row_bcast:31 row_mask:0xc bank_mask:0xf
	v_add_f32_dpp v248, v248, v248 row_bcast:31 row_mask:0xc bank_mask:0xf
	v_readlane_b32 s28, v227, 63
	v_readlane_b32 s29, v228, 63
	v_readlane_b32 s36, v229, 63
	v_readlane_b32 s37, v230, 63
	v_readlane_b32 s56, v231, 63
	v_readlane_b32 s57, v232, 63
	v_readlane_b32 s60, v233, 63
	v_readlane_b32 s61, v248, 63
	v_writelane_b32 v251, s28, 0
	v_writelane_b32 v251, s29, 1
	v_writelane_b32 v251, s36, 2
	v_writelane_b32 v251, s37, 3
	v_writelane_b32 v251, s56, 4
	v_writelane_b32 v251, s57, 5
	v_writelane_b32 v251, s60, 6
	v_writelane_b32 v251, s61, 7
	s_and_saveexec_b64 s[10:11], s[38:39]
	v_add_f32_e32 v251, v251, v168
	global_store_dword v[196:197], v251, off

; #define LAS __attribute__((address_space(3)))
; __device__ __forceinline__ float wave_sum(float v) { return rdlane(dpp_sum63(v), 63); }
; __device__ __forceinline__ void row_finalize(CArgs& A, Frame& F, int m, const f32x4 (&v)[4], int Ln) {
;     row_store_bf(WSP(bf16, WS_X) + (size_t)m * D, F.lane, v);
;     const LAS float* wig = (const LAS float*)(F.lds + WIG_OFF); const float* b_in = A.in[10] + (size_t)Ln * DIN + 3072;
;     float r[8];
; #pragma unroll
;     for (int c = 0; c < 8; ++c) { float s = 0.f;
; #pragma unroll
;         for (int j = 0; j < 4; ++j) { const f32x4 w = *(const LAS f32x4*)(wig + c * 1024 + RCOL(F.lane, j)); s += (v[j][0] * w[0] + v[j][1] * w[1]) + (v[j][2] * w[2] + v[j][3] * w[3]); }
;         r[c] = wave_sum(s); if (c & 1) asm volatile("" ::: "memory"); }
.LBB0_1713:
	s_andn2_b64 vcc, exec, s[10:11]
	s_cbranch_vccnz .LBB0_1717
	ds_read_b128 v[172:175], v94 offset:0
	ds_read_b128 v[176:179], v94 offset:16
	ds_read_b128 v[180:183], v94 offset:2048
	ds_read_b128 v[184:187], v94 offset:2064
	ds_read_b128 v[202:205], v94 offset:4096
	ds_read_b128 v[206:209], v94 offset:4112
	ds_read_b128 v[210:213], v94 offset:6144
	ds_read_b128 v[214:217], v94 offset:6160
	ds_read_b128 v[218:221], v94 offset:8192
	ds_read_b128 v[222:225], v94 offset:8208
	ds_read_b128 v[188:191], v94 offset:10240
	ds_read_b128 v[192:195], v94 offset:10256
	v_lshl_add_u64 v[238:239], s[58:59], 0, v[70:71]
	s_mov_b64 s[10:11], 0x7680000
	v_cvt_pk_bf16_f32 v240, v16, v17
	v_cvt_pk_bf16_f32 v241, v18, v19
	v_cvt_pk_bf16_f32 v242, v12, v13
	v_cvt_pk_bf16_f32 v243, v14, v15
	v_lshl_add_u64 v[238:239], v[238:239], 0, s[10:11]
	v_cvt_pk_bf16_f32 v244, v20, v21
	v_cvt_pk_bf16_f32 v245, v22, v23
	v_cvt_pk_bf16_f32 v246, v24, v25
	v_cvt_pk_bf16_f32 v247, v26, v27
	global_store_dwordx4 v[238:239], v[240:243], off
	global_store_dwordx4 v[238:239], v[244:247], off offset:1024
	v_lshl_add_u64 v[196:197], s[58:59], 0, v[68:69]
	s_waitcnt lgkmcnt(8)
	v_mul_f32_e32 v249, v17, v173
	v_mul_f32_e32 v250, v19, v175
	v_fmac_f32_e32 v249, v16, v172
	v_fmac_f32_e32 v250, v18, v174
	v_add_f32_e32 v249, v249, v250
	v_add_f32_e32 v227, 0, v249
	v_mul_f32_e32 v249, v13, v177
	v_mul_f32_e32 v250, v15, v179
	v_fmac_f32_e32 v249, v12, v176
	v_fmac_f32_e32 v250, v14, v178
	v_add_f32_e32 v249, v249, v250
	v_add_f32_e32 v227, v227, v249
	v_mul_f32_e32 v249, v21, v181
	v_mul_f32_e32 v250, v23, v183
	v_fmac_f32_e32 v249, v20, v180
	v_fmac_f32_e32 v250, v22, v182
	v_add_f32_e32 v249, v249, v250
	v_add_f32_e32 v227, v227, v249
	v_mul_f32_e32 v249, v25, v185
	v_mul_f32_e32 v250, v27, v187
	v_fmac_f32_e32 v249, v24, v184
	v_fmac_f32_e32 v250, v26, v186
	v_add_f32_e32 v249, v249, v250
	v_add_f32_e32 v227, v227, v249
	ds_read_b128 v[172:175], v94 offset:12288
	ds_read_b128 v[176:179], v94 offset:12304
	ds_read_b128 v[180:183], v94 offset:14336
	ds_read_b128 v[184:187], v94 offset:14352
	s_waitcnt lgkmcnt(8)
	v_mul_f32_e32 v249, v17, v203
	v_mul_f32_e32 v250, v19, v205
	v_fmac_f32_e32 v249, v16, v202
	v_fmac_f32_e32 v250, v18, v204
	v_add_f32_e32 v249, v249, v250
	v_add_f32_e32 v228, 0, v249
	v_mul_f32_e32 v249, v13, v207
	v_mul_f32_e32 v250, v15, v209
	v_fmac_f32_e32 v249, v12, v206
	v_fmac_f32_e32 v250, v14, v208
	v_add_f32_e32 v249, v249, v250
	v_add_f32_e32 v228, v228, v249
	v_mul_f32_e32 v249, v21, v211
	v_mul_f32_e32 v250, v23, v213
	v_fmac_f32_e32 v249, v20, v210
	v_fmac_f32_e32 v250, v22, v212
	v_add_f32_e32 v249, v249, v250
	v_add_f32_e32 v228, v228, v249
	v_mul_f32_e32 v249, v25, v215
	v_mul_f32_e32 v250, v27, v217
	v_fmac_f32_e32 v249, v24, v214
	v_fmac_f32_e32 v250, v26, v216
	v_add_f32_e32 v249, v249, v250
	v_add_f32_e32 v228, v228, v249
	ds_read_b128 v[202:205], v94 offset:16384
	ds_read_b128 v[206:209], v94 offset:16400
	ds_read_b128 v[210:213], v94 offset:18432
	ds_read_b128 v[214:217], v94 offset:18448
	s_waitcnt lgkmcnt(8)
	v_mul_f32_e32 v249, v17, v219
	v_mul_f32_e32 v250, v19, v221
	v_fmac_f32_e32 v249, v16, v218
	v_fmac_f32_e32 v250, v18, v220
	v_add_f32_e32 v249, v249, v250
	v_add_f32_e32 v229, 0, v249
	v_mul_f32_e32 v249, v13, v223
	v_mul_f32_e32 v250, v15, v225
	v_fmac_f32_e32 v249, v12, v222
	v_fmac_f32_e32 v250, v14, v224
	v_add_f32_e32 v249, v249, v250
	v_add_f32_e32 v229, v229, v249
	v_mul_f32_e32 v249, v21, v189
	v_mul_f32_e32 v250, v23, v191
	v_fmac_f32_e32 v249, v20, v188
	v_fmac_f32_e32 v250, v22, v190
	v_add_f32_e32 v249, v249, v250
	v_add_f32_e32 v229, v229, v249
	v_mul_f32_e32 v249, v25, v193
	v_mul_f32_e32 v250, v27, v195
	v_fmac_f32_e32 v249, v24, v192
	v_fmac_f32_e32 v250, v26, v194
	v_add_f32_e32 v249, v249, v250
	v_add_f32_e32 v229, v229, v249
	ds_read_b128 v[218:221], v94 offset:20480
	ds_read_b128 v[222:225], v94 offset:20496
	ds_read_b128 v[188:191], v94 offset:22528
	ds_read_b128 v[192:195], v94 offset:22544
	s_waitcnt lgkmcnt(8)
	v_mul_f32_e32 v249, v17, v173
	v_mul_f32_e32 v250, v19, v175
	v_fmac_f32_e32 v249, v16, v172
	v_fmac_f32_e32 v250, v18, v174
	v_add_f32_e32 v249, v249, v250
	v_add_f32_e32 v230, 0, v249
	v_mul_f32_e32 v249, v13, v177
	v_mul_f32_e32 v250, v15, v179
	v_fmac_f32_e32 v249, v12, v176
	v_fmac_f32_e32 v250, v14, v178
	v_add_f32_e32 v249, v249, v250
	v_add_f32_e32 v230, v230, v249
	v_mul_f32_e32 v249, v21, v181
	v_mul_f32_e32 v250, v23, v183
	v_fmac_f32_e32 v249, v20, v180
	v_fmac_f32_e32 v250, v22, v182
	v_add_f32_e32 v249, v249, v250
	v_add_f32_e32 v230, v230, v249
	v_mul_f32_e32 v249, v25, v185
	v_mul_f32_e32 v250, v27, v187
	v_fmac_f32_e32 v249, v24, v184
	v_fmac_f32_e32 v250, v26, v186
	v_add_f32_e32 v249, v249, v250
	v_add_f32_e32 v230, v230, v249
	ds_read_b128 v[172:175], v94 offset:24576
	ds_read_b128 v[176:179], v94 offset:24592
	ds_read_b128 v[180:183], v94 offset:26624
	ds_read_b128 v[184:187], v94 offset:26640
	s_waitcnt lgkmcnt(8)
	v_mul_f32_e32 v249, v17, v203
	v_mul_f32_e32 v250, v19, v205
	v_fmac_f32_e32 v249, v16, v202
	v_fmac_f32_e32 v250, v18, v204
	v_add_f32_e32 v249, v249, v250
	v_add_f32_e32 v231, 0, v249
	v_mul_f32_e32 v249, v13, v207
	v_mul_f32_e32 v250, v15, v209
	v_fmac_f32_e32 v249, v12, v206
	v_fmac_f32_e32 v250, v14, v208
	v_add_f32_e32 v249, v249, v250
	v_add_f32_e32 v231, v231, v249
	v_mul_f32_e32 v249, v21, v211
	v_mul_f32_e32 v250, v23, v213
	v_fmac_f32_e32 v249, v20, v210
	v_fmac_f32_e32 v250, v22, v212
	v_add_f32_e32 v249, v249, v250
	v_add_f32_e32 v231, v231, v249
	v_mul_f32_e32 v249, v25, v215
	v_mul_f32_e32 v250, v27, v217
	v_fmac_f32_e32 v249, v24, v214
	v_fmac_f32_e32 v250, v26, v216
	v_add_f32_e32 v249, v249, v250
	v_add_f32_e32 v231, v231, v249
	ds_read_b128 v[202:205], v94 offset:28672
	ds_read_b128 v[206:209], v94 offset:28688
	ds_read_b128 v[210:213], v94 offset:30720
	ds_read_b128 v[214:217], v94 offset:30736
	s_waitcnt lgkmcnt(8)
; #define LAS __attribute__((address_space(3)))
; __device__ __forceinline__ float wave_sum(float v) { return rdlane(dpp_sum63(v), 63); }
; __device__ __forceinline__ void row_finalize(CArgs& A, Frame& F, int m, const f32x4 (&v)[4], int Ln) {
;     ...
;     for (int c = 0; c < 8; ++c) { float s = 0.f;
; #pragma unroll
;         for (int j = 0; j < 4; ++j) { const f32x4 w = *(const LAS f32x4*)(wig + c * 1024 + RCOL(F.lane, j)); s += (v[j][0] * w[0] + v[j][1] * w[1]) + (v[j][2] * w[2] + v[j][3] * w[3]); }
;         r[c] = wave_sum(s); if (c & 1) asm volatile("" ::: "memory"); }
;     if (F.lane < 8) { float x = r[0];
; #pragma unroll
;         for (int c = 1; c < 8; ++c) x = (F.lane == c) ? r[c] : x;
;         WSP(float, WS_IGFG)[(size_t)m * 8 + F.lane] = x + b_in[F.lane]; }
	v_mul_f32_e32 v249, v17, v219
	v_mul_f32_e32 v250, v19, v221
	v_fmac_f32_e32 v249, v16, v218
	v_fmac_f32_e32 v250, v18, v220
	v_add_f32_e32 v249, v249, v250
	v_add_f32_e32 v232, 0, v249
	v_mul_f32_e32 v249, v13, v223
	v_mul_f32_e32 v250, v15, v225
	v_fmac_f32_e32 v249, v12, v222
	v_fmac_f32_e32 v250, v14, v224
	v_add_f32_e32 v249, v249, v250
	v_add_f32_e32 v232, v232, v249
	v_mul_f32_e32 v249, v21, v189
	v_mul_f32_e32 v250, v23, v191
	v_fmac_f32_e32 v249, v20, v188
	v_fmac_f32_e32 v250, v22, v190
	v_add_f32_e32 v249, v249, v250
	v_add_f32_e32 v232, v232, v249
	v_mul_f32_e32 v249, v25, v193
	v_mul_f32_e32 v250, v27, v195
	v_fmac_f32_e32 v249, v24, v192
	v_fmac_f32_e32 v250, v26, v194
	v_add_f32_e32 v249, v249, v250
	v_add_f32_e32 v232, v232, v249
	s_waitcnt lgkmcnt(4)
	v_mul_f32_e32 v249, v17, v173
	v_mul_f32_e32 v250, v19, v175
	v_fmac_f32_e32 v249, v16, v172
	v_fmac_f32_e32 v250, v18, v174
	v_add_f32_e32 v249, v249, v250
	v_add_f32_e32 v233, 0, v249
	v_mul_f32_e32 v249, v13, v177
	v_mul_f32_e32 v250, v15, v179
	v_fmac_f32_e32 v249, v12, v176
	v_fmac_f32_e32 v250, v14, v178
	v_add_f32_e32 v249, v249, v250
	v_add_f32_e32 v233, v233, v249
	v_mul_f32_e32 v249, v21, v181
	v_mul_f32_e32 v250, v23, v183
	v_fmac_f32_e32 v249, v20, v180
	v_fmac_f32_e32 v250, v22, v182
	v_add_f32_e32 v249, v249, v250
	v_add_f32_e32 v233, v233, v249
	v_mul_f32_e32 v249, v25, v185
	v_mul_f32_e32 v250, v27, v187
	v_fmac_f32_e32 v249, v24, v184
	v_fmac_f32_e32 v250, v26, v186
	v_add_f32_e32 v249, v249, v250
	v_add_f32_e32 v233, v233, v249
	s_waitcnt lgkmcnt(0)
	v_mul_f32_e32 v249, v17, v203
	v_mul_f32_e32 v250, v19, v205
	v_fmac_f32_e32 v249, v16, v202
	v_fmac_f32_e32 v250, v18, v204
	v_add_f32_e32 v249, v249, v250
	v_add_f32_e32 v248, 0, v249
	v_mul_f32_e32 v249, v13, v207
	v_mul_f32_e32 v250, v15, v209
	v_fmac_f32_e32 v249, v12, v206
	v_fmac_f32_e32 v250, v14, v208
	v_add_f32_e32 v249, v249, v250
	v_add_f32_e32 v248, v248, v249
	v_mul_f32_e32 v249, v21, v211
	v_mul_f32_e32 v250, v23, v213
	v_fmac_f32_e32 v249, v20, v210
	v_fmac_f32_e32 v250, v22, v212
	v_add_f32_e32 v249, v249, v250
	v_add_f32_e32 v248, v248, v249
	v_mul_f32_e32 v249, v25, v215
	v_mul_f32_e32 v250, v27, v217
	v_fmac_f32_e32 v249, v24, v214
	v_fmac_f32_e32 v250, v26, v216
	v_add_f32_e32 v249, v249, v250
	v_add_f32_e32 v248, v248, v249
	v_add_f32_dpp v227, v227, v227 quad_perm:[1,0,3,2] row_mask:0xf bank_mask:0xf bound_ctrl:1
	v_add_f32_dpp v228, v228, v228 quad_perm:[1,0,3,2] row_mask:0xf bank_mask:0xf bound_ctrl:1
	v_add_f32_dpp v229, v229, v229 quad_perm:[1,0,3,2] row_mask:0xf bank_mask:0xf bound_ctrl:1
	v_add_f32_dpp v230, v230, v230 quad_perm:[1,0,3,2] row_mask:0xf bank_mask:0xf bound_ctrl:1
	v_add_f32_dpp v231, v231, v231 quad_perm:[1,0,3,2] row_mask:0xf bank_mask:0xf bound_ctrl:1
	v_add_f32_dpp v232, v232, v232 quad_perm:[1,0,3,2] row_mask:0xf bank_mask:0xf bound_ctrl:1
	v_add_f32_dpp v233, v233, v233 quad_perm:[1,0,3,2] row_mask:0xf bank_mask:0xf bound_ctrl:1
	v_add_f32_dpp v248, v248, v248 quad_perm:[1,0,3,2] row_mask:0xf bank_mask:0xf bound_ctrl:1
	v_add_f32_dpp v227, v227, v227 quad_perm:[2,3,0,1] row_mask:0xf bank_mask:0xf bound_ctrl:1
	v_add_f32_dpp v228, v228, v228 quad_perm:[2,3,0,1] row_mask:0xf bank_mask:0xf bound_ctrl:1
	v_add_f32_dpp v229, v229, v229 quad_perm:[2,3,0,1] row_mask:0xf bank_mask:0xf bound_ctrl:1
	v_add_f32_dpp v230, v230, v230 quad_perm:[2,3,0,1] row_mask:0xf bank_mask:0xf bound_ctrl:1
	v_add_f32_dpp v231, v231, v231 quad_perm:[2,3,0,1] row_mask:0xf bank_mask:0xf bound_ctrl:1
	v_add_f32_dpp v232, v232, v232 quad_perm:[2,3,0,1] row_mask:0xf bank_mask:0xf bound_ctrl:1
	v_add_f32_dpp v233, v233, v233 quad_perm:[2,3,0,1] row_mask:0xf bank_mask:0xf bound_ctrl:1
	v_add_f32_dpp v248, v248, v248 quad_perm:[2,3,0,1] row_mask:0xf bank_mask:0xf bound_ctrl:1
	v_add_f32_dpp v227, v227, v227 row_half_mirror row_mask:0xf bank_mask:0xf bound_ctrl:1
	v_add_f32_dpp v228, v228, v228 row_half_mirror row_mask:0xf bank_mask:0xf bound_ctrl:1
	v_add_f32_dpp v229, v229, v229 row_half_mirror row_mask:0xf bank_mask:0xf bound_ctrl:1
	v_add_f32_dpp v230, v230, v230 row_half_mirror row_mask:0xf bank_mask:0xf bound_ctrl:1
	v_add_f32_dpp v231, v231, v231 row_half_mirror row_mask:0xf bank_mask:0xf bound_ctrl:1
	v_add_f32_dpp v232, v232, v232 row_half_mirror row_mask:0xf bank_mask:0xf bound_ctrl:1
	v_add_f32_dpp v233, v233, v233 row_half_mirror row_mask:0xf bank_mask:0xf bound_ctrl:1
	v_add_f32_dpp v248, v248, v248 row_half_mirror row_mask:0xf bank_mask:0xf bound_ctrl:1
	v_add_f32_dpp v227, v227, v227 row_mirror row_mask:0xf bank_mask:0xf bound_ctrl:1
	v_add_f32_dpp v228, v228, v228 row_mirror row_mask:0xf bank_mask:0xf bound_ctrl:1
	v_add_f32_dpp v229, v229, v229 row_mirror row_mask:0xf bank_mask:0xf bound_ctrl:1
	v_add_f32_dpp v230, v230, v230 row_mirror row_mask:0xf bank_mask:0xf bound_ctrl:1
	v_add_f32_dpp v231, v231, v231 row_mirror row_mask:0xf bank_mask:0xf bound_ctrl:1
	v_add_f32_dpp v232, v232, v232 row_mirror row_mask:0xf bank_mask:0xf bound_ctrl:1
	v_add_f32_dpp v233, v233, v233 row_mirror row_mask:0xf bank_mask:0xf bound_ctrl:1
	v_add_f32_dpp v248, v248, v248 row_mirror row_mask:0xf bank_mask:0xf bound_ctrl:1
	v_add_f32_dpp v227, v227, v227 row_bcast:15 row_mask:0xa bank_mask:0xf
	v_add_f32_dpp v228, v228, v228 row_bcast:15 row_mask:0xa bank_mask:0xf
	v_add_f32_dpp v229, v229, v229 row_bcast:15 row_mask:0xa bank_mask:0xf
	v_add_f32_dpp v230, v230, v230 row_bcast:15 row_mask:0xa bank_mask:0xf
	v_add_f32_dpp v231, v231, v231 row_bcast:15 row_mask:0xa bank_mask:0xf
	v_add_f32_dpp v232, v232, v232 row_bcast:15 row_mask:0xa bank_mask:0xf
	v_add_f32_dpp v233, v233, v233 row_bcast:15 row_mask:0xa bank_mask:0xf
	v_add_f32_dpp v248, v248, v248 row_bcast:15 row_mask:0xa bank_mask:0xf
	v_add_f32_dpp v227, v227, v227 row_bcast:31 row_mask:0xc bank_mask:0xf
	v_add_f32_dpp v228, v228, v228 row_bcast:31 row_mask:0xc bank_mask:0xf
	v_add_f32_dpp v229, v229, v229 row_bcast:31 row_mask:0xc bank_mask:0xf
	v_add_f32_dpp v230, v230, v230 row_bcast:31 row_mask:0xc bank_mask:0xf
	v_add_f32_dpp v231, v231, v231 row_bcast:31 row_mask:0xc bank_mask:0xf
	v_add_f32_dpp v232, v232, v232 row_bcast:31 row_mask:0xc bank_mask:0xf
	v_add_f32_dpp v233, v233, v233 row_bcast:31 row_mask:0xc bank_mask:0xf
	v_add_f32_dpp v248, v248, v248 row_bcast:31 row_mask:0xc bank_mask:0xf
	v_readlane_b32 s27, v227, 63
	v_readlane_b32 s28, v228, 63
	v_readlane_b32 s29, v229, 63
	v_readlane_b32 s36, v230, 63
	v_readlane_b32 s37, v231, 63
	v_readlane_b32 s56, v232, 63
	v_readlane_b32 s57, v233, 63
	v_readlane_b32 s60, v248, 63
	v_writelane_b32 v251, s27, 0
	v_writelane_b32 v251, s28, 1
	v_writelane_b32 v251, s29, 2
	v_writelane_b32 v251, s36, 3
	v_writelane_b32 v251, s37, 4
	v_writelane_b32 v251, s56, 5
	v_writelane_b32 v251, s57, 6
	v_writelane_b32 v251, s60, 7
	s_and_saveexec_b64 s[10:11], s[38:39]
	v_add_f32_e32 v251, v251, v168
	global_store_dword v[196:197], v251, off

; #define LAS __attribute__((address_space(3)))
; __device__ __forceinline__ float wave_sum(float v) { return rdlane(dpp_sum63(v), 63); }
; __device__ __forceinline__ void row_finalize(CArgs& A, Frame& F, int m, const f32x4 (&v)[4], int Ln) {
;     row_store_bf(WSP(bf16, WS_X) + (size_t)m * D, F.lane, v);
;     const LAS float* wig = (const LAS float*)(F.lds + WIG_OFF); const float* b_in = A.in[10] + (size_t)Ln * DIN + 3072;
;     float r[8];
; #pragma unroll
;     for (int c = 0; c < 8; ++c) { float s = 0.f;
; #pragma unroll
;         for (int j = 0; j < 4; ++j) { const f32x4 w = *(const LAS f32x4*)(wig + c * 1024 + RCOL(F.lane, j)); s += (v[j][0] * w[0] + v[j][1] * w[1]) + (v[j][2] * w[2] + v[j][3] * w[3]); }
;         r[c] = wave_sum(s); if (c & 1) asm volatile("" ::: "memory"); }
.LBB0_1720:
	s_andn2_b64 vcc, exec, s[10:11]
	s_cbranch_vccnz .LBB0_1696
	ds_read_b128 v[172:175], v94 offset:0
	ds_read_b128 v[176:179], v94 offset:16
	ds_read_b128 v[180:183], v94 offset:2048
	ds_read_b128 v[184:187], v94 offset:2064
	ds_read_b128 v[202:205], v94 offset:4096
	ds_read_b128 v[206:209], v94 offset:4112
	ds_read_b128 v[210:213], v94 offset:6144
	ds_read_b128 v[214:217], v94 offset:6160
	ds_read_b128 v[218:221], v94 offset:8192
	ds_read_b128 v[222:225], v94 offset:8208
	ds_read_b128 v[188:191], v94 offset:10240
	ds_read_b128 v[192:195], v94 offset:10256
	v_lshl_add_u64 v[238:239], s[58:59], 0, v[66:67]
	s_mov_b64 s[10:11], 0x7680000
	v_cvt_pk_bf16_f32 v240, v8, v9
	v_cvt_pk_bf16_f32 v241, v10, v11
	v_cvt_pk_bf16_f32 v242, v4, v5
	v_cvt_pk_bf16_f32 v243, v6, v7
	v_lshl_add_u64 v[238:239], v[238:239], 0, s[10:11]
	v_cvt_pk_bf16_f32 v244, v12, v13
	v_cvt_pk_bf16_f32 v245, v14, v15
	v_cvt_pk_bf16_f32 v246, v16, v17
	v_cvt_pk_bf16_f32 v247, v18, v19
	global_store_dwordx4 v[238:239], v[240:243], off
	global_store_dwordx4 v[238:239], v[244:247], off offset:1024
	v_lshl_add_u64 v[196:197], s[58:59], 0, v[64:65]
	s_waitcnt lgkmcnt(8)
	v_mul_f32_e32 v249, v9, v173
	v_mul_f32_e32 v250, v11, v175
	v_fmac_f32_e32 v249, v8, v172
	v_fmac_f32_e32 v250, v10, v174
	v_add_f32_e32 v249, v249, v250
	v_add_f32_e32 v227, 0, v249
	v_mul_f32_e32 v249, v5, v177
	v_mul_f32_e32 v250, v7, v179
	v_fmac_f32_e32 v249, v4, v176
	v_fmac_f32_e32 v250, v6, v178
	v_add_f32_e32 v249, v249, v250
	v_add_f32_e32 v227, v227, v249
	v_mul_f32_e32 v249, v13, v181
	v_mul_f32_e32 v250, v15, v183
	v_fmac_f32_e32 v249, v12, v180
	v_fmac_f32_e32 v250, v14, v182
	v_add_f32_e32 v249, v249, v250
	v_add_f32_e32 v227, v227, v249
	v_mul_f32_e32 v249, v17, v185
	v_mul_f32_e32 v250, v19, v187
	v_fmac_f32_e32 v249, v16, v184
	v_fmac_f32_e32 v250, v18, v186
	v_add_f32_e32 v249, v249, v250
	v_add_f32_e32 v227, v227, v249
	ds_read_b128 v[172:175], v94 offset:12288
	ds_read_b128 v[176:179], v94 offset:12304
	ds_read_b128 v[180:183], v94 offset:14336
	ds_read_b128 v[184:187], v94 offset:14352
	s_waitcnt lgkmcnt(8)
	v_mul_f32_e32 v249, v9, v203
	v_mul_f32_e32 v250, v11, v205
	v_fmac_f32_e32 v249, v8, v202
	v_fmac_f32_e32 v250, v10, v204
	v_add_f32_e32 v249, v249, v250
	v_add_f32_e32 v228, 0, v249
	v_mul_f32_e32 v249, v5, v207
	v_mul_f32_e32 v250, v7, v209
	v_fmac_f32_e32 v249, v4, v206
	v_fmac_f32_e32 v250, v6, v208
	v_add_f32_e32 v249, v249, v250
	v_add_f32_e32 v228, v228, v249
	v_mul_f32_e32 v249, v13, v211
	v_mul_f32_e32 v250, v15, v213
	v_fmac_f32_e32 v249, v12, v210
	v_fmac_f32_e32 v250, v14, v212
	v_add_f32_e32 v249, v249, v250
	v_add_f32_e32 v228, v228, v249
	v_mul_f32_e32 v249, v17, v215
	v_mul_f32_e32 v250, v19, v217
	v_fmac_f32_e32 v249, v16, v214
	v_fmac_f32_e32 v250, v18, v216
	v_add_f32_e32 v249, v249, v250
	v_add_f32_e32 v228, v228, v249
	ds_read_b128 v[202:205], v94 offset:16384
	ds_read_b128 v[206:209], v94 offset:16400
	ds_read_b128 v[210:213], v94 offset:18432
	ds_read_b128 v[214:217], v94 offset:18448
	s_waitcnt lgkmcnt(8)
	v_mul_f32_e32 v249, v9, v219
	v_mul_f32_e32 v250, v11, v221
	v_fmac_f32_e32 v249, v8, v218
	v_fmac_f32_e32 v250, v10, v220
	v_add_f32_e32 v249, v249, v250
	v_add_f32_e32 v229, 0, v249
	v_mul_f32_e32 v249, v5, v223
	v_mul_f32_e32 v250, v7, v225
	v_fmac_f32_e32 v249, v4, v222
	v_fmac_f32_e32 v250, v6, v224
	v_add_f32_e32 v249, v249, v250
	v_add_f32_e32 v229, v229, v249
	v_mul_f32_e32 v249, v13, v189
	v_mul_f32_e32 v250, v15, v191
	v_fmac_f32_e32 v249, v12, v188
	v_fmac_f32_e32 v250, v14, v190
	v_add_f32_e32 v249, v249, v250
	v_add_f32_e32 v229, v229, v249
	v_mul_f32_e32 v249, v17, v193
	v_mul_f32_e32 v250, v19, v195
	v_fmac_f32_e32 v249, v16, v192
	v_fmac_f32_e32 v250, v18, v194
	v_add_f32_e32 v249, v249, v250
	v_add_f32_e32 v229, v229, v249
	ds_read_b128 v[218:221], v94 offset:20480
	ds_read_b128 v[222:225], v94 offset:20496
	ds_read_b128 v[188:191], v94 offset:22528
	ds_read_b128 v[192:195], v94 offset:22544
	s_waitcnt lgkmcnt(8)
	v_mul_f32_e32 v249, v9, v173
	v_mul_f32_e32 v250, v11, v175
	v_fmac_f32_e32 v249, v8, v172
	v_fmac_f32_e32 v250, v10, v174
	v_add_f32_e32 v249, v249, v250
	v_add_f32_e32 v230, 0, v249
	v_mul_f32_e32 v249, v5, v177
	v_mul_f32_e32 v250, v7, v179
	v_fmac_f32_e32 v249, v4, v176
	v_fmac_f32_e32 v250, v6, v178
	v_add_f32_e32 v249, v249, v250
	v_add_f32_e32 v230, v230, v249
	v_mul_f32_e32 v249, v13, v181
	v_mul_f32_e32 v250, v15, v183
	v_fmac_f32_e32 v249, v12, v180
	v_fmac_f32_e32 v250, v14, v182
	v_add_f32_e32 v249, v249, v250
	v_add_f32_e32 v230, v230, v249
	v_mul_f32_e32 v249, v17, v185
	v_mul_f32_e32 v250, v19, v187
	v_fmac_f32_e32 v249, v16, v184
	v_fmac_f32_e32 v250, v18, v186
	v_add_f32_e32 v249, v249, v250
	v_add_f32_e32 v230, v230, v249
	ds_read_b128 v[172:175], v94 offset:24576
	ds_read_b128 v[176:179], v94 offset:24592
	ds_read_b128 v[180:183], v94 offset:26624
	ds_read_b128 v[184:187], v94 offset:26640
	s_waitcnt lgkmcnt(8)
	v_mul_f32_e32 v249, v9, v203
	v_mul_f32_e32 v250, v11, v205
	v_fmac_f32_e32 v249, v8, v202
	v_fmac_f32_e32 v250, v10, v204
	v_add_f32_e32 v249, v249, v250
	v_add_f32_e32 v231, 0, v249
	v_mul_f32_e32 v249, v5, v207
	v_mul_f32_e32 v250, v7, v209
	v_fmac_f32_e32 v249, v4, v206
	v_fmac_f32_e32 v250, v6, v208
	v_add_f32_e32 v249, v249, v250
	v_add_f32_e32 v231, v231, v249
	v_mul_f32_e32 v249, v13, v211
	v_mul_f32_e32 v250, v15, v213
	v_fmac_f32_e32 v249, v12, v210
	v_fmac_f32_e32 v250, v14, v212
	v_add_f32_e32 v249, v249, v250
	v_add_f32_e32 v231, v231, v249
	v_mul_f32_e32 v249, v17, v215
	v_mul_f32_e32 v250, v19, v217
	v_fmac_f32_e32 v249, v16, v214
	v_fmac_f32_e32 v250, v18, v216
	v_add_f32_e32 v249, v249, v250
	v_add_f32_e32 v231, v231, v249
	ds_read_b128 v[202:205], v94 offset:28672
	ds_read_b128 v[206:209], v94 offset:28688
	ds_read_b128 v[210:213], v94 offset:30720
	ds_read_b128 v[214:217], v94 offset:30736
	s_waitcnt lgkmcnt(8)
; #define LAS __attribute__((address_space(3)))
; __device__ __forceinline__ float wave_sum(float v) { return rdlane(dpp_sum63(v), 63); }
; __device__ __forceinline__ void row_finalize(CArgs& A, Frame& F, int m, const f32x4 (&v)[4], int Ln) {
;     ...
;     for (int c = 0; c < 8; ++c) { float s = 0.f;
; #pragma unroll
;         for (int j = 0; j < 4; ++j) { const f32x4 w = *(const LAS f32x4*)(wig + c * 1024 + RCOL(F.lane, j)); s += (v[j][0] * w[0] + v[j][1] * w[1]) + (v[j][2] * w[2] + v[j][3] * w[3]); }
;         r[c] = wave_sum(s); if (c & 1) asm volatile("" ::: "memory"); }
;     if (F.lane < 8) { float x = r[0];
; #pragma unroll
;         for (int c = 1; c < 8; ++c) x = (F.lane == c) ? r[c] : x;
;         WSP(float, WS_IGFG)[(size_t)m * 8 + F.lane] = x + b_in[F.lane]; }
	v_mul_f32_e32 v249, v9, v219
	v_mul_f32_e32 v250, v11, v221
	v_fmac_f32_e32 v249, v8, v218
	v_fmac_f32_e32 v250, v10, v220
	v_add_f32_e32 v249, v249, v250
	v_add_f32_e32 v232, 0, v249
	v_mul_f32_e32 v249, v5, v223
	v_mul_f32_e32 v250, v7, v225
	v_fmac_f32_e32 v249, v4, v222
	v_fmac_f32_e32 v250, v6, v224
	v_add_f32_e32 v249, v249, v250
	v_add_f32_e32 v232, v232, v249
	v_mul_f32_e32 v249, v13, v189
	v_mul_f32_e32 v250, v15, v191
	v_fmac_f32_e32 v249, v12, v188
	v_fmac_f32_e32 v250, v14, v190
	v_add_f32_e32 v249, v249, v250
	v_add_f32_e32 v232, v232, v249
	v_mul_f32_e32 v249, v17, v193
	v_mul_f32_e32 v250, v19, v195
	v_fmac_f32_e32 v249, v16, v192
	v_fmac_f32_e32 v250, v18, v194
	v_add_f32_e32 v249, v249, v250
	v_add_f32_e32 v232, v232, v249
	s_waitcnt lgkmcnt(4)
	v_mul_f32_e32 v249, v9, v173
	v_mul_f32_e32 v250, v11, v175
	v_fmac_f32_e32 v249, v8, v172
	v_fmac_f32_e32 v250, v10, v174
	v_add_f32_e32 v249, v249, v250
	v_add_f32_e32 v233, 0, v249
	v_mul_f32_e32 v249, v5, v177
	v_mul_f32_e32 v250, v7, v179
	v_fmac_f32_e32 v249, v4, v176
	v_fmac_f32_e32 v250, v6, v178
	v_add_f32_e32 v249, v249, v250
	v_add_f32_e32 v233, v233, v249
	v_mul_f32_e32 v249, v13, v181
	v_mul_f32_e32 v250, v15, v183
	v_fmac_f32_e32 v249, v12, v180
	v_fmac_f32_e32 v250, v14, v182
	v_add_f32_e32 v249, v249, v250
	v_add_f32_e32 v233, v233, v249
	v_mul_f32_e32 v249, v17, v185
	v_mul_f32_e32 v250, v19, v187
	v_fmac_f32_e32 v249, v16, v184
	v_fmac_f32_e32 v250, v18, v186
	v_add_f32_e32 v249, v249, v250
	v_add_f32_e32 v233, v233, v249
	s_waitcnt lgkmcnt(0)
	v_mul_f32_e32 v249, v9, v203
	v_mul_f32_e32 v250, v11, v205
	v_fmac_f32_e32 v249, v8, v202
	v_fmac_f32_e32 v250, v10, v204
	v_add_f32_e32 v249, v249, v250
	v_add_f32_e32 v248, 0, v249
	v_mul_f32_e32 v249, v5, v207
	v_mul_f32_e32 v250, v7, v209
	v_fmac_f32_e32 v249, v4, v206
	v_fmac_f32_e32 v250, v6, v208
	v_add_f32_e32 v249, v249, v250
	v_add_f32_e32 v248, v248, v249
	v_mul_f32_e32 v249, v13, v211
	v_mul_f32_e32 v250, v15, v213
	v_fmac_f32_e32 v249, v12, v210
	v_fmac_f32_e32 v250, v14, v212
	v_add_f32_e32 v249, v249, v250
	v_add_f32_e32 v248, v248, v249
	v_mul_f32_e32 v249, v17, v215
	v_mul_f32_e32 v250, v19, v217
	v_fmac_f32_e32 v249, v16, v214
	v_fmac_f32_e32 v250, v18, v216
	v_add_f32_e32 v249, v249, v250
	v_add_f32_e32 v248, v248, v249
	v_add_f32_dpp v227, v227, v227 quad_perm:[1,0,3,2] row_mask:0xf bank_mask:0xf bound_ctrl:1
	v_add_f32_dpp v228, v228, v228 quad_perm:[1,0,3,2] row_mask:0xf bank_mask:0xf bound_ctrl:1
	v_add_f32_dpp v229, v229, v229 quad_perm:[1,0,3,2] row_mask:0xf bank_mask:0xf bound_ctrl:1
	v_add_f32_dpp v230, v230, v230 quad_perm:[1,0,3,2] row_mask:0xf bank_mask:0xf bound_ctrl:1
	v_add_f32_dpp v231, v231, v231 quad_perm:[1,0,3,2] row_mask:0xf bank_mask:0xf bound_ctrl:1
	v_add_f32_dpp v232, v232, v232 quad_perm:[1,0,3,2] row_mask:0xf bank_mask:0xf bound_ctrl:1
	v_add_f32_dpp v233, v233, v233 quad_perm:[1,0,3,2] row_mask:0xf bank_mask:0xf bound_ctrl:1
	v_add_f32_dpp v248, v248, v248 quad_perm:[1,0,3,2] row_mask:0xf bank_mask:0xf bound_ctrl:1
	v_add_f32_dpp v227, v227, v227 quad_perm:[2,3,0,1] row_mask:0xf bank_mask:0xf bound_ctrl:1
	v_add_f32_dpp v228, v228, v228 quad_perm:[2,3,0,1] row_mask:0xf bank_mask:0xf bound_ctrl:1
	v_add_f32_dpp v229, v229, v229 quad_perm:[2,3,0,1] row_mask:0xf bank_mask:0xf bound_ctrl:1
	v_add_f32_dpp v230, v230, v230 quad_perm:[2,3,0,1] row_mask:0xf bank_mask:0xf bound_ctrl:1
	v_add_f32_dpp v231, v231, v231 quad_perm:[2,3,0,1] row_mask:0xf bank_mask:0xf bound_ctrl:1
	v_add_f32_dpp v232, v232, v232 quad_perm:[2,3,0,1] row_mask:0xf bank_mask:0xf bound_ctrl:1
	v_add_f32_dpp v233, v233, v233 quad_perm:[2,3,0,1] row_mask:0xf bank_mask:0xf bound_ctrl:1
	v_add_f32_dpp v248, v248, v248 quad_perm:[2,3,0,1] row_mask:0xf bank_mask:0xf bound_ctrl:1
	v_add_f32_dpp v227, v227, v227 row_half_mirror row_mask:0xf bank_mask:0xf bound_ctrl:1
	v_add_f32_dpp v228, v228, v228 row_half_mirror row_mask:0xf bank_mask:0xf bound_ctrl:1
	v_add_f32_dpp v229, v229, v229 row_half_mirror row_mask:0xf bank_mask:0xf bound_ctrl:1
	v_add_f32_dpp v230, v230, v230 row_half_mirror row_mask:0xf bank_mask:0xf bound_ctrl:1
	v_add_f32_dpp v231, v231, v231 row_half_mirror row_mask:0xf bank_mask:0xf bound_ctrl:1
	v_add_f32_dpp v232, v232, v232 row_half_mirror row_mask:0xf bank_mask:0xf bound_ctrl:1
	v_add_f32_dpp v233, v233, v233 row_half_mirror row_mask:0xf bank_mask:0xf bound_ctrl:1
	v_add_f32_dpp v248, v248, v248 row_half_mirror row_mask:0xf bank_mask:0xf bound_ctrl:1
	v_add_f32_dpp v227, v227, v227 row_mirror row_mask:0xf bank_mask:0xf bound_ctrl:1
	v_add_f32_dpp v228, v228, v228 row_mirror row_mask:0xf bank_mask:0xf bound_ctrl:1
	v_add_f32_dpp v229, v229, v229 row_mirror row_mask:0xf bank_mask:0xf bound_ctrl:1
	v_add_f32_dpp v230, v230, v230 row_mirror row_mask:0xf bank_mask:0xf bound_ctrl:1
	v_add_f32_dpp v231, v231, v231 row_mirror row_mask:0xf bank_mask:0xf bound_ctrl:1
	v_add_f32_dpp v232, v232, v232 row_mirror row_mask:0xf bank_mask:0xf bound_ctrl:1
	v_add_f32_dpp v233, v233, v233 row_mirror row_mask:0xf bank_mask:0xf bound_ctrl:1
	v_add_f32_dpp v248, v248, v248 row_mirror row_mask:0xf bank_mask:0xf bound_ctrl:1
	v_add_f32_dpp v227, v227, v227 row_bcast:15 row_mask:0xa bank_mask:0xf
	v_add_f32_dpp v228, v228, v228 row_bcast:15 row_mask:0xa bank_mask:0xf
	v_add_f32_dpp v229, v229, v229 row_bcast:15 row_mask:0xa bank_mask:0xf
	v_add_f32_dpp v230, v230, v230 row_bcast:15 row_mask:0xa bank_mask:0xf
	v_add_f32_dpp v231, v231, v231 row_bcast:15 row_mask:0xa bank_mask:0xf
	v_add_f32_dpp v232, v232, v232 row_bcast:15 row_mask:0xa bank_mask:0xf
	v_add_f32_dpp v233, v233, v233 row_bcast:15 row_mask:0xa bank_mask:0xf
	v_add_f32_dpp v248, v248, v248 row_bcast:15 row_mask:0xa bank_mask:0xf
	v_add_f32_dpp v227, v227, v227 row_bcast:31 row_mask:0xc bank_mask:0xf
	v_add_f32_dpp v228, v228, v228 row_bcast:31 row_mask:0xc bank_mask:0xf
	v_add_f32_dpp v229, v229, v229 row_bcast:31 row_mask:0xc bank_mask:0xf
	v_add_f32_dpp v230, v230, v230 row_bcast:31 row_mask:0xc bank_mask:0xf
	v_add_f32_dpp v231, v231, v231 row_bcast:31 row_mask:0xc bank_mask:0xf
	v_add_f32_dpp v232, v232, v232 row_bcast:31 row_mask:0xc bank_mask:0xf
	v_add_f32_dpp v233, v233, v233 row_bcast:31 row_mask:0xc bank_mask:0xf
	v_add_f32_dpp v248, v248, v248 row_bcast:31 row_mask:0xc bank_mask:0xf
	v_readlane_b32 s7, v227, 63
	v_readlane_b32 s27, v228, 63
	v_readlane_b32 s28, v229, 63
	v_readlane_b32 s29, v230, 63
	v_readlane_b32 s36, v231, 63
	v_readlane_b32 s37, v232, 63
	v_readlane_b32 s54, v233, 63
	v_readlane_b32 s55, v248, 63
	v_writelane_b32 v251, s7, 0
	v_writelane_b32 v251, s27, 1
	v_writelane_b32 v251, s28, 2
	v_writelane_b32 v251, s29, 3
	v_writelane_b32 v251, s36, 4
	v_writelane_b32 v251, s37, 5
	v_writelane_b32 v251, s54, 6
	v_writelane_b32 v251, s55, 7
	s_and_saveexec_b64 s[10:11], s[38:39]
	v_add_f32_e32 v251, v251, v168
	global_store_dword v[196:197], v251, off
	s_branch .LBB0_1695
